# GDOWN meta-row skinny GEMM (KS=11): all 33 operand loads + the 2 scale loads issued before the first MFMA (was 11 serialized load/wait/MFMA round trips), LDS reduction reads batched
# speedup vs baseline: 1.0136x; 1.0051x over previous
.LBB0_225:
	v_add_u32_e32 v4, s2, v160
	v_mad_i64_i32 v[2:3], s[18:19], v4, s15, 0
	v_lshl_add_u64 v[8:9], v[2:3], 1, v[12:13]
	v_add_u32_e32 v2, 16, v4
	v_mad_i64_i32 v[2:3], s[18:19], v2, s15, 0
	v_lshl_add_u64 v[2:3], v[2:3], 1, v[12:13]
	global_load_dwordx4 v[36:39], v[8:9], off
	global_load_dwordx4 v[40:43], v[10:11], off
	global_load_dwordx4 v[44:47], v[2:3], off
	global_load_dwordx4 v[48:51], v[8:9], off offset:64
	global_load_dwordx4 v[52:55], v[10:11], off offset:64
	global_load_dwordx4 v[56:59], v[2:3], off offset:64
	global_load_dwordx4 v[60:63], v[8:9], off offset:128
	global_load_dwordx4 v[64:67], v[10:11], off offset:128
	global_load_dwordx4 v[68:71], v[2:3], off offset:128
	global_load_dwordx4 v[72:75], v[8:9], off offset:192
	global_load_dwordx4 v[76:79], v[10:11], off offset:192
	global_load_dwordx4 v[80:83], v[2:3], off offset:192
	global_load_dwordx4 v[84:87], v[8:9], off offset:256
	global_load_dwordx4 v[88:91], v[10:11], off offset:256
	global_load_dwordx4 v[92:95], v[2:3], off offset:256
	global_load_dwordx4 v[96:99], v[8:9], off offset:320
	global_load_dwordx4 v[100:103], v[10:11], off offset:320
	global_load_dwordx4 v[114:117], v[2:3], off offset:320
	global_load_dwordx4 v[118:121], v[8:9], off offset:384
	global_load_dwordx4 v[130:133], v[10:11], off offset:384
	global_load_dwordx4 v[134:137], v[2:3], off offset:384
	global_load_dwordx4 v[138:141], v[8:9], off offset:448
	global_load_dwordx4 v[142:145], v[10:11], off offset:448
	global_load_dwordx4 v[106:109], v[2:3], off offset:448
	global_load_dwordx4 v[110:113], v[8:9], off offset:512
	global_load_dwordx4 v[122:125], v[10:11], off offset:512
	global_load_dwordx4 v[126:129], v[2:3], off offset:512
	global_load_dwordx4 v[164:167], v[8:9], off offset:576
	global_load_dwordx4 v[168:171], v[10:11], off offset:576
	global_load_dwordx4 v[172:175], v[2:3], off offset:576
	global_load_dwordx4 v[176:179], v[8:9], off offset:640
	global_load_dwordx4 v[180:183], v[10:11], off offset:640
	global_load_dwordx4 v[184:187], v[2:3], off offset:640
	v_add_u32_e32 v24, s2, v19
	v_ashrrev_i32_e32 v25, 31, v24
	v_add_u32_e32 v26, 16, v24
	v_ashrrev_i32_e32 v27, 31, v26
	v_lshl_add_u64 v[4:5], v[24:25], 2, s[44:45]
	v_lshl_add_u64 v[6:7], v[26:27], 2, s[44:45]
	global_load_dwordx4 v[28:31], v[4:5], off
	global_load_dwordx4 v[32:35], v[6:7], off
	s_andn2_b64 vcc, exec, s[40:41]
	s_waitcnt vmcnt(33)
	v_mfma_f32_16x16x32_bf16 v[2:5], v[36:39], v[40:43], 0
	s_waitcnt vmcnt(32)
	v_mfma_f32_16x16x32_bf16 v[6:9], v[44:47], v[40:43], 0
	s_waitcnt vmcnt(30)
	v_mfma_f32_16x16x32_bf16 v[2:5], v[48:51], v[52:55], v[2:5]
	s_waitcnt vmcnt(29)
	v_mfma_f32_16x16x32_bf16 v[6:9], v[56:59], v[52:55], v[6:9]
	s_waitcnt vmcnt(27)
	v_mfma_f32_16x16x32_bf16 v[2:5], v[60:63], v[64:67], v[2:5]
	s_waitcnt vmcnt(26)
	v_mfma_f32_16x16x32_bf16 v[6:9], v[68:71], v[64:67], v[6:9]
	s_waitcnt vmcnt(24)
	v_mfma_f32_16x16x32_bf16 v[2:5], v[72:75], v[76:79], v[2:5]
	s_waitcnt vmcnt(23)
	v_mfma_f32_16x16x32_bf16 v[6:9], v[80:83], v[76:79], v[6:9]
	s_waitcnt vmcnt(21)
	v_mfma_f32_16x16x32_bf16 v[2:5], v[84:87], v[88:91], v[2:5]
	s_waitcnt vmcnt(20)
	v_mfma_f32_16x16x32_bf16 v[6:9], v[92:95], v[88:91], v[6:9]
	s_waitcnt vmcnt(18)
	v_mfma_f32_16x16x32_bf16 v[2:5], v[96:99], v[100:103], v[2:5]
	s_waitcnt vmcnt(17)
	v_mfma_f32_16x16x32_bf16 v[6:9], v[114:117], v[100:103], v[6:9]
	s_waitcnt vmcnt(15)
	v_mfma_f32_16x16x32_bf16 v[2:5], v[118:121], v[130:133], v[2:5]
	s_waitcnt vmcnt(14)
	v_mfma_f32_16x16x32_bf16 v[6:9], v[134:137], v[130:133], v[6:9]
	s_waitcnt vmcnt(12)
	v_mfma_f32_16x16x32_bf16 v[2:5], v[138:141], v[142:145], v[2:5]
	s_waitcnt vmcnt(11)
	v_mfma_f32_16x16x32_bf16 v[6:9], v[106:109], v[142:145], v[6:9]
	s_waitcnt vmcnt(9)
	v_mfma_f32_16x16x32_bf16 v[2:5], v[110:113], v[122:125], v[2:5]
	s_waitcnt vmcnt(8)
	v_mfma_f32_16x16x32_bf16 v[6:9], v[126:129], v[122:125], v[6:9]
	s_waitcnt vmcnt(6)
	v_mfma_f32_16x16x32_bf16 v[2:5], v[164:167], v[168:171], v[2:5]
	s_waitcnt vmcnt(5)
	v_mfma_f32_16x16x32_bf16 v[6:9], v[172:175], v[168:171], v[6:9]
	s_waitcnt vmcnt(3)
	v_mfma_f32_16x16x32_bf16 v[2:5], v[176:179], v[180:183], v[2:5]
	s_waitcnt vmcnt(2)
	v_mfma_f32_16x16x32_bf16 v[6:9], v[184:187], v[180:183], v[6:9]
	s_nop 6
	ds_write_b128 v0, v[2:5]
	ds_write_b128 v0, v[6:9] offset:16
	s_waitcnt lgkmcnt(0)
	s_barrier
	s_cbranch_vccnz .LBB0_224
	v_add_u32_e32 v17, 0, v18
	ds_read_b128 v[36:39], v17 offset:2048
	ds_read_b128 v[40:43], v17 offset:2064
	ds_read_b128 v[44:47], v17 offset:4096
	ds_read_b128 v[48:51], v17 offset:4112
	ds_read_b128 v[52:55], v17 offset:6144
	ds_read_b128 v[56:59], v17 offset:6160
	ds_read_b128 v[60:63], v17 offset:8192
	ds_read_b128 v[64:67], v17 offset:8208
	ds_read_b128 v[68:71], v17 offset:10240
	ds_read_b128 v[72:75], v17 offset:10256
	ds_read_b128 v[76:79], v17 offset:12288
	ds_read_b128 v[80:83], v17 offset:12304
	ds_read_b128 v[84:87], v17 offset:14336
	ds_read_b128 v[88:91], v17 offset:14352
	s_waitcnt lgkmcnt(13)
	v_pk_add_f32 v[22:23], v[4:5], v[38:39]
	v_pk_add_f32 v[20:21], v[2:3], v[36:37]
	s_waitcnt lgkmcnt(12)
	v_pk_add_f32 v[8:9], v[8:9], v[42:43]
	v_pk_add_f32 v[6:7], v[6:7], v[40:41]
	s_waitcnt lgkmcnt(11)
	v_pk_add_f32 v[22:23], v[22:23], v[46:47]
	v_pk_add_f32 v[20:21], v[20:21], v[44:45]
	s_waitcnt lgkmcnt(10)
	v_pk_add_f32 v[8:9], v[8:9], v[50:51]
	v_pk_add_f32 v[6:7], v[6:7], v[48:49]
	s_waitcnt lgkmcnt(9)
	v_pk_add_f32 v[22:23], v[22:23], v[54:55]
	v_pk_add_f32 v[20:21], v[20:21], v[52:53]
	s_waitcnt lgkmcnt(8)
	v_pk_add_f32 v[8:9], v[8:9], v[58:59]
	v_pk_add_f32 v[6:7], v[6:7], v[56:57]
	s_waitcnt lgkmcnt(7)
	v_pk_add_f32 v[22:23], v[22:23], v[62:63]
	v_pk_add_f32 v[20:21], v[20:21], v[60:61]
	s_waitcnt lgkmcnt(6)
	v_pk_add_f32 v[8:9], v[8:9], v[66:67]
	v_pk_add_f32 v[6:7], v[6:7], v[64:65]
	s_waitcnt lgkmcnt(5)
	v_pk_add_f32 v[22:23], v[22:23], v[70:71]
	v_pk_add_f32 v[20:21], v[20:21], v[68:69]
	s_waitcnt lgkmcnt(4)
	v_pk_add_f32 v[8:9], v[8:9], v[74:75]
	v_pk_add_f32 v[6:7], v[6:7], v[72:73]
	s_waitcnt lgkmcnt(3)
	v_pk_add_f32 v[22:23], v[22:23], v[78:79]
	v_pk_add_f32 v[20:21], v[20:21], v[76:77]
	s_waitcnt lgkmcnt(2)
	v_pk_add_f32 v[8:9], v[8:9], v[82:83]
	v_pk_add_f32 v[6:7], v[6:7], v[80:81]
	s_waitcnt lgkmcnt(1)
	v_pk_add_f32 v[22:23], v[22:23], v[86:87]
	v_pk_add_f32 v[20:21], v[20:21], v[84:85]
	s_waitcnt lgkmcnt(0)
	v_pk_add_f32 v[8:9], v[8:9], v[90:91]
	v_pk_add_f32 v[6:7], v[6:7], v[88:89]
	v_lshl_add_u64 v[24:25], v[24:25], 1, v[14:15]
	s_waitcnt vmcnt(0)
	v_pk_mul_f32 v[20:21], v[20:21], v[28:29]
	v_pk_mul_f32 v[22:23], v[22:23], v[30:31]
	v_pk_mul_f32 v[2:3], v[6:7], v[32:33]
	v_cvt_pk_bf16_f32 v6, v20, v21
	v_cvt_pk_bf16_f32 v7, v22, v23
	global_store_dwordx2 v[24:25], v[6:7], off
	v_lshl_add_u64 v[6:7], v[26:27], 1, v[14:15]
	v_pk_mul_f32 v[4:5], v[8:9], v[34:35]
	v_cvt_pk_bf16_f32 v8, v2, v3
	v_mul_f32_e32 v3, v3, v3
	v_cvt_pk_bf16_f32 v9, v4, v5
	global_store_dwordx2 v[6:7], v[8:9], off
	v_mul_f32_e32 v6, v21, v21
	v_mul_f32_e32 v7, v23, v23
	v_fmac_f32_e32 v6, v20, v20
	v_fmac_f32_e32 v7, v22, v22
	v_add_f32_e32 v6, v6, v7
	v_fmac_f32_e32 v3, v2, v2
	v_add_f32_e32 v2, v6, v3
	v_mul_f32_e32 v3, v5, v5
	v_fmac_f32_e32 v3, v4, v4
	v_and_b32_e32 v4, 64, v231
	v_add_f32_e32 v2, v3, v2
	v_xor_b32_e32 v3, 16, v231
	v_add_u32_e32 v4, 64, v4
	v_cmp_lt_i32_e32 vcc, v3, v4
	s_nop 1
	v_cndmask_b32_e32 v3, v231, v3, vcc
	v_lshlrev_b32_e32 v3, 2, v3
	ds_bpermute_b32 v3, v3, v2
	s_waitcnt lgkmcnt(0)
	v_add_f32_e32 v2, v2, v3
	v_xor_b32_e32 v3, 32, v231
	v_cmp_lt_i32_e32 vcc, v3, v4
	s_nop 1
	v_cndmask_b32_e32 v3, v231, v3, vcc
	v_lshlrev_b32_e32 v3, 2, v3
	ds_bpermute_b32 v3, v3, v2
	s_and_saveexec_b64 s[42:43], s[38:39]
	s_cbranch_execz .LBB0_223
	v_ashrrev_i32_e32 v17, 31, v16
	v_lshl_add_u64 v[4:5], v[16:17], 2, s[26:27]
	s_waitcnt lgkmcnt(0)
	v_add_f32_e32 v2, v2, v3
	global_store_dword v[4:5], v2, off
	s_branch .LBB0_223
